# grid barrier: non-leader workgroups issue their L1 invalidate (buffer_inv sc1) before polling for the release instead of after it
# speedup vs baseline: 1.0141x; 1.0141x over previous
; __device__ __forceinline__ unsigned xb_ld(unsigned* p)              { return __hip_atomic_load(p, __ATOMIC_RELAXED, __HIP_MEMORY_SCOPE_AGENT); }
; __device__ __forceinline__ unsigned xb_add(unsigned* p, unsigned v) { return __hip_atomic_fetch_add(p, v, __ATOMIC_RELAXED, __HIP_MEMORY_SCOPE_AGENT); }
; #define XB_SPIN(cond, bar) do { unsigned _sp = 0; while (cond) { __builtin_amdgcn_s_sleep(1); \
;     if ((++_sp & 255u) == 0u) { if (xb_ld(&(bar)[XB_TMO])) break; if (_sp > XB_SPIN_CAP) { atomicAdd(&(bar)[XB_TMO], 1u); break; } } } } while (0)
; __device__ __forceinline__ void xcd_barrier(const XcdBarrier& b) {
;     ...
;         const unsigned old = xb_add(&bar[XB_XSUB(b.x)], 1u);
;         const unsigned gen = old / nloc;
;         if (old + 1u == (gen + 1u) * nloc) {
;             __builtin_amdgcn_fence(__ATOMIC_RELEASE, "agent");
;             asm volatile("s_waitcnt vmcnt(0)" ::: "memory");
;             const unsigned og = xb_add(&bar[XB_TOP], 1u);
;             const unsigned tg = og / nx;
;             if (og + 1u == (tg + 1u) * nx) xb_add(&bar[XB_TOPGEN], 1u);
;             else XB_SPIN(xb_ld(&bar[XB_TOPGEN]) == tg, bar);
;             __builtin_amdgcn_fence(__ATOMIC_ACQUIRE, "agent");
;             xb_add(&bar[XB_XGEN(b.x)], 1u);
;             asm volatile("s_waitcnt vmcnt(0)" ::: "memory");
;         } else {
;             XB_SPIN(xb_ld(&bar[XB_XGEN(b.x)]) == gen, bar);
;             __builtin_amdgcn_fence(__ATOMIC_ACQUIRE, "agent");
.LBB0_63:
	s_or_b64 exec, exec, s[12:13]
	v_cvt_f32_u32_e32 v5, v3
	s_waitcnt vmcnt(0)
	v_readfirstlane_b32 s0, v4
	v_sub_u32_e32 v4, 0, v3
	v_rcp_iflag_f32_e32 v5, v5
	v_add_u32_e32 v6, s0, v2
	v_mul_f32_e32 v5, 0x4f7ffffe, v5
	v_cvt_u32_f32_e32 v5, v5
	v_mul_lo_u32 v2, v4, v5
	v_mul_hi_u32 v2, v5, v2
	v_add_u32_e32 v2, v5, v2
	v_mul_hi_u32 v2, v6, v2
	v_mul_lo_u32 v4, v2, v3
	v_sub_u32_e32 v4, v6, v4
	v_add_u32_e32 v5, 1, v2
	v_cmp_ge_u32_e32 vcc, v4, v3
	s_nop 1
	v_cndmask_b32_e32 v2, v2, v5, vcc
	v_sub_u32_e32 v5, v4, v3
	v_cndmask_b32_e32 v4, v4, v5, vcc
	v_add_u32_e32 v5, 1, v2
	v_cmp_ge_u32_e32 vcc, v4, v3
	v_add_u32_e32 v4, 1, v6
	s_nop 0
	v_cndmask_b32_e32 v2, v2, v5, vcc
	v_mul_lo_u32 v5, v3, v2
	v_add_u32_e32 v3, v5, v3
	v_cmp_ne_u32_e32 vcc, v4, v3
	s_and_saveexec_b64 s[0:1], vcc
	s_xor_b64 s[18:19], exec, s[0:1]
	s_cbranch_execz .LBB0_77
	s_waitcnt lgkmcnt(0)
	buffer_inv sc1
	v_mov_b32_e32 v1, 0x2000
	global_load_dword v1, v1, s[14:15] offset:1024 sc1
	s_add_u32 s22, s14, 0x2400
	s_addc_u32 s23, s15, 0
	s_waitcnt vmcnt(0)
	v_cmp_eq_u32_e32 vcc, v1, v2
	s_and_saveexec_b64 s[0:1], vcc
	s_cbranch_execz .LBB0_76
	s_add_u32 s12, s78, 0x4200
	s_addc_u32 s13, s79, 0
	s_mov_b32 s3, 1
	s_mov_b64 s[24:25], 0
	v_mov_b32_e32 v1, 0
	s_branch .LBB0_67

; __device__ __forceinline__ unsigned xb_ld(unsigned* p)              { return __hip_atomic_load(p, __ATOMIC_RELAXED, __HIP_MEMORY_SCOPE_AGENT); }
; #define XB_SPIN(cond, bar) do { unsigned _sp = 0; while (cond) { __builtin_amdgcn_s_sleep(1); \
;     if ((++_sp & 255u) == 0u) { if (xb_ld(&(bar)[XB_TMO])) break; if (_sp > XB_SPIN_CAP) { atomicAdd(&(bar)[XB_TMO], 1u); break; } } } } while (0)
; __device__ __forceinline__ void xcd_barrier(const XcdBarrier& b) {
;     ...
;             XB_SPIN(xb_ld(&bar[XB_XGEN(b.x)]) == gen, bar);
;             __builtin_amdgcn_fence(__ATOMIC_ACQUIRE, "agent");
;             asm volatile("s_waitcnt vmcnt(0)" ::: "memory");
.LBB0_76:
	s_or_b64 exec, exec, s[0:1]
	s_waitcnt vmcnt(0)
	s_waitcnt vmcnt(0)

; __device__ __forceinline__ unsigned xb_ld(unsigned* p)              { return __hip_atomic_load(p, __ATOMIC_RELAXED, __HIP_MEMORY_SCOPE_AGENT); }
; __device__ __forceinline__ unsigned xb_add(unsigned* p, unsigned v) { return __hip_atomic_fetch_add(p, v, __ATOMIC_RELAXED, __HIP_MEMORY_SCOPE_AGENT); }
; #define XB_SPIN(cond, bar) do { unsigned _sp = 0; while (cond) { __builtin_amdgcn_s_sleep(1); \
;     if ((++_sp & 255u) == 0u) { if (xb_ld(&(bar)[XB_TMO])) break; if (_sp > XB_SPIN_CAP) { atomicAdd(&(bar)[XB_TMO], 1u); break; } } } } while (0)
; __device__ __forceinline__ void xcd_barrier(const XcdBarrier& b) {
;     ...
;         const unsigned old = xb_add(&bar[XB_XSUB(b.x)], 1u);
;         const unsigned gen = old / nloc;
;         if (old + 1u == (gen + 1u) * nloc) {
;             __builtin_amdgcn_fence(__ATOMIC_RELEASE, "agent");
;             asm volatile("s_waitcnt vmcnt(0)" ::: "memory");
;             const unsigned og = xb_add(&bar[XB_TOP], 1u);
;             const unsigned tg = og / nx;
;             if (og + 1u == (tg + 1u) * nx) xb_add(&bar[XB_TOPGEN], 1u);
;             else XB_SPIN(xb_ld(&bar[XB_TOPGEN]) == tg, bar);
;             __builtin_amdgcn_fence(__ATOMIC_ACQUIRE, "agent");
;             xb_add(&bar[XB_XGEN(b.x)], 1u);
;             asm volatile("s_waitcnt vmcnt(0)" ::: "memory");
;         } else {
;             XB_SPIN(xb_ld(&bar[XB_XGEN(b.x)]) == gen, bar);
;             __builtin_amdgcn_fence(__ATOMIC_ACQUIRE, "agent");
.LBB0_217:
	s_or_b64 exec, exec, s[12:13]
	v_cvt_f32_u32_e32 v5, v3
	s_waitcnt vmcnt(0)
	v_readfirstlane_b32 s0, v4
	v_sub_u32_e32 v4, 0, v3
	v_rcp_iflag_f32_e32 v5, v5
	v_add_u32_e32 v6, s0, v2
	v_mul_f32_e32 v5, 0x4f7ffffe, v5
	v_cvt_u32_f32_e32 v5, v5
	v_mul_lo_u32 v2, v4, v5
	v_mul_hi_u32 v2, v5, v2
	v_add_u32_e32 v2, v5, v2
	v_mul_hi_u32 v2, v6, v2
	v_mul_lo_u32 v4, v2, v3
	v_sub_u32_e32 v4, v6, v4
	v_add_u32_e32 v5, 1, v2
	v_cmp_ge_u32_e32 vcc, v4, v3
	s_nop 1
	v_cndmask_b32_e32 v2, v2, v5, vcc
	v_sub_u32_e32 v5, v4, v3
	v_cndmask_b32_e32 v4, v4, v5, vcc
	v_add_u32_e32 v5, 1, v2
	v_cmp_ge_u32_e32 vcc, v4, v3
	v_add_u32_e32 v4, 1, v6
	s_nop 0
	v_cndmask_b32_e32 v2, v2, v5, vcc
	v_mul_lo_u32 v5, v3, v2
	v_add_u32_e32 v3, v5, v3
	v_cmp_ne_u32_e32 vcc, v4, v3
	s_and_saveexec_b64 s[0:1], vcc
	s_xor_b64 s[18:19], exec, s[0:1]
	s_cbranch_execz .LBB0_231
	s_waitcnt lgkmcnt(0)
	buffer_inv sc1
	v_mov_b32_e32 v1, 0x2000
	global_load_dword v1, v1, s[6:7] offset:1024 sc1
	s_add_u32 s20, s6, 0x2400
	s_addc_u32 s21, s7, 0
	s_waitcnt vmcnt(0)
	v_cmp_eq_u32_e32 vcc, v1, v2
	s_and_saveexec_b64 s[0:1], vcc
	s_cbranch_execz .LBB0_230
	s_add_u32 s12, s78, 0x4200
	s_addc_u32 s13, s79, 0
	s_mov_b32 s3, 1
	s_mov_b64 s[26:27], 0
	v_mov_b32_e32 v1, 0
	s_branch .LBB0_221

; __device__ __forceinline__ unsigned xb_ld(unsigned* p)              { return __hip_atomic_load(p, __ATOMIC_RELAXED, __HIP_MEMORY_SCOPE_AGENT); }
; __device__ __forceinline__ unsigned xb_add(unsigned* p, unsigned v) { return __hip_atomic_fetch_add(p, v, __ATOMIC_RELAXED, __HIP_MEMORY_SCOPE_AGENT); }
; #define XB_SPIN(cond, bar) do { unsigned _sp = 0; while (cond) { __builtin_amdgcn_s_sleep(1); \
;     if ((++_sp & 255u) == 0u) { if (xb_ld(&(bar)[XB_TMO])) break; if (_sp > XB_SPIN_CAP) { atomicAdd(&(bar)[XB_TMO], 1u); break; } } } } while (0)
; __device__ __forceinline__ void xcd_barrier(const XcdBarrier& b) {
;     ...
;         const unsigned old = xb_add(&bar[XB_XSUB(b.x)], 1u);
;         const unsigned gen = old / nloc;
;         if (old + 1u == (gen + 1u) * nloc) {
;             __builtin_amdgcn_fence(__ATOMIC_RELEASE, "agent");
;             asm volatile("s_waitcnt vmcnt(0)" ::: "memory");
;             const unsigned og = xb_add(&bar[XB_TOP], 1u);
;             const unsigned tg = og / nx;
;             if (og + 1u == (tg + 1u) * nx) xb_add(&bar[XB_TOPGEN], 1u);
;             else XB_SPIN(xb_ld(&bar[XB_TOPGEN]) == tg, bar);
;             __builtin_amdgcn_fence(__ATOMIC_ACQUIRE, "agent");
;             xb_add(&bar[XB_XGEN(b.x)], 1u);
;             asm volatile("s_waitcnt vmcnt(0)" ::: "memory");
;         } else {
;             XB_SPIN(xb_ld(&bar[XB_XGEN(b.x)]) == gen, bar);
;             __builtin_amdgcn_fence(__ATOMIC_ACQUIRE, "agent");
.LBB0_331:
	s_or_b64 exec, exec, s[12:13]
	v_cvt_f32_u32_e32 v5, v3
	s_waitcnt vmcnt(0)
	v_readfirstlane_b32 s0, v4
	v_sub_u32_e32 v4, 0, v3
	v_rcp_iflag_f32_e32 v5, v5
	v_add_u32_e32 v6, s0, v2
	v_mul_f32_e32 v5, 0x4f7ffffe, v5
	v_cvt_u32_f32_e32 v5, v5
	v_mul_lo_u32 v2, v4, v5
	v_mul_hi_u32 v2, v5, v2
	v_add_u32_e32 v2, v5, v2
	v_mul_hi_u32 v2, v6, v2
	v_mul_lo_u32 v4, v2, v3
	v_sub_u32_e32 v4, v6, v4
	v_add_u32_e32 v5, 1, v2
	v_cmp_ge_u32_e32 vcc, v4, v3
	s_nop 1
	v_cndmask_b32_e32 v2, v2, v5, vcc
	v_sub_u32_e32 v5, v4, v3
	v_cndmask_b32_e32 v4, v4, v5, vcc
	v_add_u32_e32 v5, 1, v2
	v_cmp_ge_u32_e32 vcc, v4, v3
	v_add_u32_e32 v4, 1, v6
	s_nop 0
	v_cndmask_b32_e32 v2, v2, v5, vcc
	v_mul_lo_u32 v5, v3, v2
	v_add_u32_e32 v3, v5, v3
	v_cmp_ne_u32_e32 vcc, v4, v3
	s_and_saveexec_b64 s[0:1], vcc
	s_xor_b64 s[20:21], exec, s[0:1]
	s_cbranch_execz .LBB0_345
	s_waitcnt lgkmcnt(0)
	buffer_inv sc1
	v_mov_b32_e32 v1, 0x2000
	global_load_dword v1, v1, s[6:7] offset:1024 sc1
	s_add_u32 s26, s6, 0x2400
	s_addc_u32 s27, s7, 0
	s_waitcnt vmcnt(0)
	v_cmp_eq_u32_e32 vcc, v1, v2
	s_and_saveexec_b64 s[0:1], vcc
	s_cbranch_execz .LBB0_344
	s_add_u32 s12, s78, 0x4200
	s_addc_u32 s13, s79, 0
	s_mov_b32 s3, 1
	s_mov_b64 s[28:29], 0
	v_mov_b32_e32 v1, 0
	s_branch .LBB0_335

; __device__ __forceinline__ unsigned xb_ld(unsigned* p)              { return __hip_atomic_load(p, __ATOMIC_RELAXED, __HIP_MEMORY_SCOPE_AGENT); }
; __device__ __forceinline__ unsigned xb_add(unsigned* p, unsigned v) { return __hip_atomic_fetch_add(p, v, __ATOMIC_RELAXED, __HIP_MEMORY_SCOPE_AGENT); }
; #define XB_SPIN(cond, bar) do { unsigned _sp = 0; while (cond) { __builtin_amdgcn_s_sleep(1); \
;     if ((++_sp & 255u) == 0u) { if (xb_ld(&(bar)[XB_TMO])) break; if (_sp > XB_SPIN_CAP) { atomicAdd(&(bar)[XB_TMO], 1u); break; } } } } while (0)
; __device__ __forceinline__ void xcd_barrier(const XcdBarrier& b) {
;     ...
;         const unsigned old = xb_add(&bar[XB_XSUB(b.x)], 1u);
;         const unsigned gen = old / nloc;
;         if (old + 1u == (gen + 1u) * nloc) {
;             __builtin_amdgcn_fence(__ATOMIC_RELEASE, "agent");
;             asm volatile("s_waitcnt vmcnt(0)" ::: "memory");
;             const unsigned og = xb_add(&bar[XB_TOP], 1u);
;             const unsigned tg = og / nx;
;             if (og + 1u == (tg + 1u) * nx) xb_add(&bar[XB_TOPGEN], 1u);
;             else XB_SPIN(xb_ld(&bar[XB_TOPGEN]) == tg, bar);
;             __builtin_amdgcn_fence(__ATOMIC_ACQUIRE, "agent");
;             xb_add(&bar[XB_XGEN(b.x)], 1u);
;             asm volatile("s_waitcnt vmcnt(0)" ::: "memory");
;         } else {
;             XB_SPIN(xb_ld(&bar[XB_XGEN(b.x)]) == gen, bar);
;             __builtin_amdgcn_fence(__ATOMIC_ACQUIRE, "agent");
.LBB0_524:
	s_or_b64 exec, exec, s[8:9]
	v_cvt_f32_u32_e32 v5, v3
	s_waitcnt vmcnt(0)
	v_readfirstlane_b32 s0, v4
	v_sub_u32_e32 v4, 0, v3
	v_rcp_iflag_f32_e32 v5, v5
	v_add_u32_e32 v6, s0, v2
	v_mul_f32_e32 v5, 0x4f7ffffe, v5
	v_cvt_u32_f32_e32 v5, v5
	v_mul_lo_u32 v2, v4, v5
	v_mul_hi_u32 v2, v5, v2
	v_add_u32_e32 v2, v5, v2
	v_mul_hi_u32 v2, v6, v2
	v_mul_lo_u32 v4, v2, v3
	v_sub_u32_e32 v4, v6, v4
	v_add_u32_e32 v5, 1, v2
	v_cmp_ge_u32_e32 vcc, v4, v3
	s_nop 1
	v_cndmask_b32_e32 v2, v2, v5, vcc
	v_sub_u32_e32 v5, v4, v3
	v_cndmask_b32_e32 v4, v4, v5, vcc
	v_add_u32_e32 v5, 1, v2
	v_cmp_ge_u32_e32 vcc, v4, v3
	v_add_u32_e32 v4, 1, v6
	s_nop 0
	v_cndmask_b32_e32 v2, v2, v5, vcc
	v_mul_lo_u32 v5, v3, v2
	v_add_u32_e32 v3, v5, v3
	v_cmp_ne_u32_e32 vcc, v4, v3
	s_and_saveexec_b64 s[0:1], vcc
	s_xor_b64 s[8:9], exec, s[0:1]
	s_cbranch_execz .LBB0_538
	s_waitcnt lgkmcnt(0)
	buffer_inv sc1
	v_mov_b32_e32 v1, 0x2000
	global_load_dword v1, v1, s[6:7] offset:1024 sc1
	s_add_u32 s28, s6, 0x2400
	s_addc_u32 s29, s7, 0
	s_waitcnt vmcnt(0)
	v_cmp_eq_u32_e32 vcc, v1, v2
	s_and_saveexec_b64 s[0:1], vcc
	s_cbranch_execz .LBB0_537
	s_add_u32 s12, s78, 0x4200
	s_addc_u32 s13, s79, 0
	s_mov_b32 s3, 1
	s_mov_b64 s[30:31], 0
	v_mov_b32_e32 v1, 0
	s_branch .LBB0_528

; __device__ __forceinline__ unsigned xb_ld(unsigned* p)              { return __hip_atomic_load(p, __ATOMIC_RELAXED, __HIP_MEMORY_SCOPE_AGENT); }
; __device__ __forceinline__ unsigned xb_add(unsigned* p, unsigned v) { return __hip_atomic_fetch_add(p, v, __ATOMIC_RELAXED, __HIP_MEMORY_SCOPE_AGENT); }
; #define XB_SPIN(cond, bar) do { unsigned _sp = 0; while (cond) { __builtin_amdgcn_s_sleep(1); \
;     if ((++_sp & 255u) == 0u) { if (xb_ld(&(bar)[XB_TMO])) break; if (_sp > XB_SPIN_CAP) { atomicAdd(&(bar)[XB_TMO], 1u); break; } } } } while (0)
; __device__ __forceinline__ void xcd_barrier(const XcdBarrier& b) {
;     ...
;         const unsigned old = xb_add(&bar[XB_XSUB(b.x)], 1u);
;         const unsigned gen = old / nloc;
;         if (old + 1u == (gen + 1u) * nloc) {
;             __builtin_amdgcn_fence(__ATOMIC_RELEASE, "agent");
;             asm volatile("s_waitcnt vmcnt(0)" ::: "memory");
;             const unsigned og = xb_add(&bar[XB_TOP], 1u);
;             const unsigned tg = og / nx;
;             if (og + 1u == (tg + 1u) * nx) xb_add(&bar[XB_TOPGEN], 1u);
;             else XB_SPIN(xb_ld(&bar[XB_TOPGEN]) == tg, bar);
;             __builtin_amdgcn_fence(__ATOMIC_ACQUIRE, "agent");
;             xb_add(&bar[XB_XGEN(b.x)], 1u);
;             asm volatile("s_waitcnt vmcnt(0)" ::: "memory");
;         } else {
;             XB_SPIN(xb_ld(&bar[XB_XGEN(b.x)]) == gen, bar);
;             __builtin_amdgcn_fence(__ATOMIC_ACQUIRE, "agent");
.LBB0_641:
	s_or_b64 exec, exec, s[8:9]
	v_cvt_f32_u32_e32 v5, v3
	s_waitcnt vmcnt(0)
	v_readfirstlane_b32 s0, v4
	v_sub_u32_e32 v4, 0, v3
	v_rcp_iflag_f32_e32 v5, v5
	v_add_u32_e32 v6, s0, v2
	v_mul_f32_e32 v5, 0x4f7ffffe, v5
	v_cvt_u32_f32_e32 v5, v5
	v_mul_lo_u32 v2, v4, v5
	v_mul_hi_u32 v2, v5, v2
	v_add_u32_e32 v2, v5, v2
	v_mul_hi_u32 v2, v6, v2
	v_mul_lo_u32 v4, v2, v3
	v_sub_u32_e32 v4, v6, v4
	v_add_u32_e32 v5, 1, v2
	v_cmp_ge_u32_e32 vcc, v4, v3
	s_nop 1
	v_cndmask_b32_e32 v2, v2, v5, vcc
	v_sub_u32_e32 v5, v4, v3
	v_cndmask_b32_e32 v4, v4, v5, vcc
	v_add_u32_e32 v5, 1, v2
	v_cmp_ge_u32_e32 vcc, v4, v3
	v_add_u32_e32 v4, 1, v6
	s_nop 0
	v_cndmask_b32_e32 v2, v2, v5, vcc
	v_mul_lo_u32 v5, v3, v2
	v_add_u32_e32 v3, v5, v3
	v_cmp_ne_u32_e32 vcc, v4, v3
	s_and_saveexec_b64 s[0:1], vcc
	s_xor_b64 s[8:9], exec, s[0:1]
	s_cbranch_execz .LBB0_655
	s_waitcnt lgkmcnt(0)
	buffer_inv sc1
	v_mov_b32_e32 v1, 0x2000
	global_load_dword v1, v1, s[6:7] offset:1024 sc1
	s_add_u32 s42, s6, 0x2400
	s_addc_u32 s43, s7, 0
	s_waitcnt vmcnt(0)
	v_cmp_eq_u32_e32 vcc, v1, v2
	s_and_saveexec_b64 s[0:1], vcc
	s_cbranch_execz .LBB0_654
	s_add_u32 s12, s78, 0x4200
	s_addc_u32 s13, s79, 0
	s_mov_b32 s3, 1
	s_mov_b64 s[44:45], 0
	v_mov_b32_e32 v1, 0
	s_branch .LBB0_645

; __device__ __forceinline__ unsigned xb_ld(unsigned* p)              { return __hip_atomic_load(p, __ATOMIC_RELAXED, __HIP_MEMORY_SCOPE_AGENT); }
; __device__ __forceinline__ unsigned xb_add(unsigned* p, unsigned v) { return __hip_atomic_fetch_add(p, v, __ATOMIC_RELAXED, __HIP_MEMORY_SCOPE_AGENT); }
; #define XB_SPIN(cond, bar) do { unsigned _sp = 0; while (cond) { __builtin_amdgcn_s_sleep(1); \
;     if ((++_sp & 255u) == 0u) { if (xb_ld(&(bar)[XB_TMO])) break; if (_sp > XB_SPIN_CAP) { atomicAdd(&(bar)[XB_TMO], 1u); break; } } } } while (0)
; __device__ __forceinline__ void xcd_barrier(const XcdBarrier& b) {
;     ...
;         unsigned nloc = b.st[0], nx = b.st[1];
;         if (nloc == 0u) { xcd_barrier_complete(bar, b.x, nloc, nx); b.st[0] = nloc; b.st[1] = nx; }
;         const unsigned old = xb_add(&bar[XB_XSUB(b.x)], 1u);
;         const unsigned gen = old / nloc;
;         if (old + 1u == (gen + 1u) * nloc) {
;             __builtin_amdgcn_fence(__ATOMIC_RELEASE, "agent");
;             asm volatile("s_waitcnt vmcnt(0)" ::: "memory");
;             const unsigned og = xb_add(&bar[XB_TOP], 1u);
;             const unsigned tg = og / nx;
;             if (og + 1u == (tg + 1u) * nx) xb_add(&bar[XB_TOPGEN], 1u);
;             else XB_SPIN(xb_ld(&bar[XB_TOPGEN]) == tg, bar);
;             __builtin_amdgcn_fence(__ATOMIC_ACQUIRE, "agent");
;             xb_add(&bar[XB_XGEN(b.x)], 1u);
;             asm volatile("s_waitcnt vmcnt(0)" ::: "memory");
;         } else {
;             XB_SPIN(xb_ld(&bar[XB_XGEN(b.x)]) == gen, bar);
.LBB0_723:
	s_or_b64 exec, exec, s[8:9]
	v_cvt_f32_u32_e32 v5, v3
	s_waitcnt vmcnt(0)
	v_readfirstlane_b32 s0, v4
	v_sub_u32_e32 v4, 0, v3
	v_rcp_iflag_f32_e32 v5, v5
	v_add_u32_e32 v6, s0, v2
	v_mul_f32_e32 v5, 0x4f7ffffe, v5
	v_cvt_u32_f32_e32 v5, v5
	v_mul_lo_u32 v2, v4, v5
	v_mul_hi_u32 v2, v5, v2
	v_add_u32_e32 v2, v5, v2
	v_mul_hi_u32 v2, v6, v2
	v_mul_lo_u32 v4, v2, v3
	v_sub_u32_e32 v4, v6, v4
	v_add_u32_e32 v5, 1, v2
	v_cmp_ge_u32_e32 vcc, v4, v3
	s_nop 1
	v_cndmask_b32_e32 v2, v2, v5, vcc
	v_sub_u32_e32 v5, v4, v3
	v_cndmask_b32_e32 v4, v4, v5, vcc
	v_add_u32_e32 v5, 1, v2
	v_cmp_ge_u32_e32 vcc, v4, v3
	v_add_u32_e32 v4, 1, v6
	s_nop 0
	v_cndmask_b32_e32 v2, v2, v5, vcc
	v_mul_lo_u32 v5, v3, v2
	v_add_u32_e32 v3, v5, v3
	v_cmp_ne_u32_e32 vcc, v4, v3
	s_and_saveexec_b64 s[0:1], vcc
	s_xor_b64 s[8:9], exec, s[0:1]
	s_cbranch_execz .LBB0_737
	s_waitcnt lgkmcnt(0)
	buffer_inv sc1
	v_mov_b32_e32 v1, 0x2000
	global_load_dword v1, v1, s[6:7] offset:1024 sc1
	s_add_u32 s36, s6, 0x2400
	s_addc_u32 s37, s7, 0
	s_waitcnt vmcnt(0)
	v_cmp_eq_u32_e32 vcc, v1, v2
	s_and_saveexec_b64 s[0:1], vcc
	s_cbranch_execz .LBB0_736
	s_add_u32 s12, s78, 0x4200
	s_addc_u32 s13, s79, 0
	s_mov_b32 s3, 1
	s_mov_b64 s[40:41], 0
	v_mov_b32_e32 v1, 0
	s_branch .LBB0_727

; __device__ __forceinline__ unsigned xb_ld(unsigned* p)              { return __hip_atomic_load(p, __ATOMIC_RELAXED, __HIP_MEMORY_SCOPE_AGENT); }
; __device__ __forceinline__ unsigned xb_add(unsigned* p, unsigned v) { return __hip_atomic_fetch_add(p, v, __ATOMIC_RELAXED, __HIP_MEMORY_SCOPE_AGENT); }
; #define XB_SPIN(cond, bar) do { unsigned _sp = 0; while (cond) { __builtin_amdgcn_s_sleep(1); \
;     if ((++_sp & 255u) == 0u) { if (xb_ld(&(bar)[XB_TMO])) break; if (_sp > XB_SPIN_CAP) { atomicAdd(&(bar)[XB_TMO], 1u); break; } } } } while (0)
; __device__ __forceinline__ void xcd_barrier(const XcdBarrier& b) {
;     ...
;         unsigned nloc = b.st[0], nx = b.st[1];
;         if (nloc == 0u) { xcd_barrier_complete(bar, b.x, nloc, nx); b.st[0] = nloc; b.st[1] = nx; }
;         const unsigned old = xb_add(&bar[XB_XSUB(b.x)], 1u);
;         const unsigned gen = old / nloc;
;         if (old + 1u == (gen + 1u) * nloc) {
;             __builtin_amdgcn_fence(__ATOMIC_RELEASE, "agent");
;             asm volatile("s_waitcnt vmcnt(0)" ::: "memory");
;             const unsigned og = xb_add(&bar[XB_TOP], 1u);
;             const unsigned tg = og / nx;
;             if (og + 1u == (tg + 1u) * nx) xb_add(&bar[XB_TOPGEN], 1u);
;             else XB_SPIN(xb_ld(&bar[XB_TOPGEN]) == tg, bar);
;             __builtin_amdgcn_fence(__ATOMIC_ACQUIRE, "agent");
;             xb_add(&bar[XB_XGEN(b.x)], 1u);
;             asm volatile("s_waitcnt vmcnt(0)" ::: "memory");
;         } else {
;             XB_SPIN(xb_ld(&bar[XB_XGEN(b.x)]) == gen, bar);
.LBB0_977:
	s_or_b64 exec, exec, s[8:9]
	v_cvt_f32_u32_e32 v5, v3
	s_waitcnt vmcnt(0)
	v_readfirstlane_b32 s0, v4
	v_sub_u32_e32 v4, 0, v3
	v_rcp_iflag_f32_e32 v5, v5
	v_add_u32_e32 v6, s0, v2
	v_mul_f32_e32 v5, 0x4f7ffffe, v5
	v_cvt_u32_f32_e32 v5, v5
	v_mul_lo_u32 v2, v4, v5
	v_mul_hi_u32 v2, v5, v2
	v_add_u32_e32 v2, v5, v2
	v_mul_hi_u32 v2, v6, v2
	v_mul_lo_u32 v4, v2, v3
	v_sub_u32_e32 v4, v6, v4
	v_add_u32_e32 v5, 1, v2
	v_cmp_ge_u32_e32 vcc, v4, v3
	s_nop 1
	v_cndmask_b32_e32 v2, v2, v5, vcc
	v_sub_u32_e32 v5, v4, v3
	v_cndmask_b32_e32 v4, v4, v5, vcc
	v_add_u32_e32 v5, 1, v2
	v_cmp_ge_u32_e32 vcc, v4, v3
	v_add_u32_e32 v4, 1, v6
	s_nop 0
	v_cndmask_b32_e32 v2, v2, v5, vcc
	v_mul_lo_u32 v5, v3, v2
	v_add_u32_e32 v3, v5, v3
	v_cmp_ne_u32_e32 vcc, v4, v3
	s_and_saveexec_b64 s[0:1], vcc
	s_xor_b64 s[8:9], exec, s[0:1]
	s_cbranch_execz .LBB0_991
	s_waitcnt lgkmcnt(0)
	buffer_inv sc1
	v_mov_b32_e32 v1, 0x2000
	global_load_dword v1, v1, s[6:7] offset:1024 sc1
	s_add_u32 s14, s6, 0x2400
	s_addc_u32 s15, s7, 0
	s_waitcnt vmcnt(0)
	v_cmp_eq_u32_e32 vcc, v1, v2
	s_and_saveexec_b64 s[0:1], vcc
	s_cbranch_execz .LBB0_990
	s_add_u32 s12, s78, 0x4200
	s_addc_u32 s13, s79, 0
	s_mov_b32 s3, 1
	s_mov_b64 s[22:23], 0
	v_mov_b32_e32 v1, 0
	s_branch .LBB0_981

; __device__ __forceinline__ unsigned xb_ld(unsigned* p)              { return __hip_atomic_load(p, __ATOMIC_RELAXED, __HIP_MEMORY_SCOPE_AGENT); }
; __device__ __forceinline__ unsigned xb_add(unsigned* p, unsigned v) { return __hip_atomic_fetch_add(p, v, __ATOMIC_RELAXED, __HIP_MEMORY_SCOPE_AGENT); }
; #define XB_SPIN(cond, bar) do { unsigned _sp = 0; while (cond) { __builtin_amdgcn_s_sleep(1); \
;     if ((++_sp & 255u) == 0u) { if (xb_ld(&(bar)[XB_TMO])) break; if (_sp > XB_SPIN_CAP) { atomicAdd(&(bar)[XB_TMO], 1u); break; } } } } while (0)
; __device__ __forceinline__ void xcd_barrier(const XcdBarrier& b) {
;     ...
;         unsigned nloc = b.st[0], nx = b.st[1];
;         if (nloc == 0u) { xcd_barrier_complete(bar, b.x, nloc, nx); b.st[0] = nloc; b.st[1] = nx; }
;         const unsigned old = xb_add(&bar[XB_XSUB(b.x)], 1u);
;         const unsigned gen = old / nloc;
;         if (old + 1u == (gen + 1u) * nloc) {
;             __builtin_amdgcn_fence(__ATOMIC_RELEASE, "agent");
;             asm volatile("s_waitcnt vmcnt(0)" ::: "memory");
;             const unsigned og = xb_add(&bar[XB_TOP], 1u);
;             const unsigned tg = og / nx;
;             if (og + 1u == (tg + 1u) * nx) xb_add(&bar[XB_TOPGEN], 1u);
;             else XB_SPIN(xb_ld(&bar[XB_TOPGEN]) == tg, bar);
;             __builtin_amdgcn_fence(__ATOMIC_ACQUIRE, "agent");
;             xb_add(&bar[XB_XGEN(b.x)], 1u);
;             asm volatile("s_waitcnt vmcnt(0)" ::: "memory");
;         } else {
;             XB_SPIN(xb_ld(&bar[XB_XGEN(b.x)]) == gen, bar);
.LBB0_1132:
	s_or_b64 exec, exec, s[8:9]
	v_cvt_f32_u32_e32 v5, v3
	s_waitcnt vmcnt(0)
	v_readfirstlane_b32 s0, v4
	v_sub_u32_e32 v4, 0, v3
	v_rcp_iflag_f32_e32 v5, v5
	v_add_u32_e32 v6, s0, v2
	v_mul_f32_e32 v5, 0x4f7ffffe, v5
	v_cvt_u32_f32_e32 v5, v5
	v_mul_lo_u32 v2, v4, v5
	v_mul_hi_u32 v2, v5, v2
	v_add_u32_e32 v2, v5, v2
	v_mul_hi_u32 v2, v6, v2
	v_mul_lo_u32 v4, v2, v3
	v_sub_u32_e32 v4, v6, v4
	v_add_u32_e32 v5, 1, v2
	v_cmp_ge_u32_e32 vcc, v4, v3
	s_nop 1
	v_cndmask_b32_e32 v2, v2, v5, vcc
	v_sub_u32_e32 v5, v4, v3
	v_cndmask_b32_e32 v4, v4, v5, vcc
	v_add_u32_e32 v5, 1, v2
	v_cmp_ge_u32_e32 vcc, v4, v3
	v_add_u32_e32 v4, 1, v6
	s_nop 0
	v_cndmask_b32_e32 v2, v2, v5, vcc
	v_mul_lo_u32 v5, v3, v2
	v_add_u32_e32 v3, v5, v3
	v_cmp_ne_u32_e32 vcc, v4, v3
	s_and_saveexec_b64 s[0:1], vcc
	s_xor_b64 s[8:9], exec, s[0:1]
	s_cbranch_execz .LBB0_1146
	s_waitcnt lgkmcnt(0)
	buffer_inv sc1
	v_mov_b32_e32 v1, 0x2000
	global_load_dword v1, v1, s[6:7] offset:1024 sc1
	s_add_u32 s12, s6, 0x2400
	s_addc_u32 s13, s7, 0
	s_waitcnt vmcnt(0)
	v_cmp_eq_u32_e32 vcc, v1, v2
	s_and_saveexec_b64 s[0:1], vcc
	s_cbranch_execz .LBB0_1145
	s_add_u32 s10, s78, 0x4200
	s_addc_u32 s11, s79, 0
	s_mov_b32 s3, 1
	s_mov_b64 s[14:15], 0
	v_mov_b32_e32 v1, 0
	s_branch .LBB0_1136

; __device__ __forceinline__ unsigned xb_ld(unsigned* p)              { return __hip_atomic_load(p, __ATOMIC_RELAXED, __HIP_MEMORY_SCOPE_AGENT); }
; __device__ __forceinline__ unsigned xb_add(unsigned* p, unsigned v) { return __hip_atomic_fetch_add(p, v, __ATOMIC_RELAXED, __HIP_MEMORY_SCOPE_AGENT); }
; #define XB_SPIN(cond, bar) do { unsigned _sp = 0; while (cond) { __builtin_amdgcn_s_sleep(1); \
;     if ((++_sp & 255u) == 0u) { if (xb_ld(&(bar)[XB_TMO])) break; if (_sp > XB_SPIN_CAP) { atomicAdd(&(bar)[XB_TMO], 1u); break; } } } } while (0)
; __device__ __forceinline__ void xcd_barrier(const XcdBarrier& b) {
;     ...
;         unsigned nloc = b.st[0], nx = b.st[1];
;         if (nloc == 0u) { xcd_barrier_complete(bar, b.x, nloc, nx); b.st[0] = nloc; b.st[1] = nx; }
;         const unsigned old = xb_add(&bar[XB_XSUB(b.x)], 1u);
;         const unsigned gen = old / nloc;
;         if (old + 1u == (gen + 1u) * nloc) {
;             __builtin_amdgcn_fence(__ATOMIC_RELEASE, "agent");
;             asm volatile("s_waitcnt vmcnt(0)" ::: "memory");
;             const unsigned og = xb_add(&bar[XB_TOP], 1u);
;             const unsigned tg = og / nx;
;             if (og + 1u == (tg + 1u) * nx) xb_add(&bar[XB_TOPGEN], 1u);
;             else XB_SPIN(xb_ld(&bar[XB_TOPGEN]) == tg, bar);
;             __builtin_amdgcn_fence(__ATOMIC_ACQUIRE, "agent");
;             xb_add(&bar[XB_XGEN(b.x)], 1u);
;             asm volatile("s_waitcnt vmcnt(0)" ::: "memory");
;         } else {
;             XB_SPIN(xb_ld(&bar[XB_XGEN(b.x)]) == gen, bar);
.LBB0_1204:
	s_or_b64 exec, exec, s[12:13]
	v_cvt_f32_u32_e32 v5, v3
	s_waitcnt vmcnt(0)
	v_readfirstlane_b32 s3, v4
	v_sub_u32_e32 v4, 0, v3
	v_rcp_iflag_f32_e32 v5, v5
	v_add_u32_e32 v6, s3, v2
	v_mul_f32_e32 v5, 0x4f7ffffe, v5
	v_cvt_u32_f32_e32 v5, v5
	v_mul_lo_u32 v2, v4, v5
	v_mul_hi_u32 v2, v5, v2
	v_add_u32_e32 v2, v5, v2
	v_mul_hi_u32 v2, v6, v2
	v_mul_lo_u32 v4, v2, v3
	v_sub_u32_e32 v4, v6, v4
	v_add_u32_e32 v5, 1, v2
	v_cmp_ge_u32_e32 vcc, v4, v3
	s_nop 1
	v_cndmask_b32_e32 v2, v2, v5, vcc
	v_sub_u32_e32 v5, v4, v3
	v_cndmask_b32_e32 v4, v4, v5, vcc
	v_add_u32_e32 v5, 1, v2
	v_cmp_ge_u32_e32 vcc, v4, v3
	v_add_u32_e32 v4, 1, v6
	s_nop 0
	v_cndmask_b32_e32 v2, v2, v5, vcc
	v_mul_lo_u32 v5, v3, v2
	v_add_u32_e32 v3, v5, v3
	v_cmp_ne_u32_e32 vcc, v4, v3
	s_and_saveexec_b64 s[6:7], vcc
	s_xor_b64 s[6:7], exec, s[6:7]
	s_cbranch_execz .LBB0_1218
	s_waitcnt lgkmcnt(0)
	buffer_inv sc1
	v_mov_b32_e32 v1, 0x2000
	global_load_dword v1, v1, s[0:1] offset:1024 sc1
	s_add_u32 s16, s0, 0x2400
	s_addc_u32 s17, s1, 0
	s_waitcnt vmcnt(0)
	v_cmp_eq_u32_e32 vcc, v1, v2
	s_and_saveexec_b64 s[12:13], vcc
	s_cbranch_execz .LBB0_1217
	s_add_u32 s14, s78, 0x4200
	s_addc_u32 s15, s79, 0
	s_mov_b32 s3, 1
	s_mov_b64 s[20:21], 0
	v_mov_b32_e32 v1, 0
	s_branch .LBB0_1208

; __device__ __forceinline__ unsigned xb_ld(unsigned* p)              { return __hip_atomic_load(p, __ATOMIC_RELAXED, __HIP_MEMORY_SCOPE_AGENT); }
; #define XB_SPIN(cond, bar) do { unsigned _sp = 0; while (cond) { __builtin_amdgcn_s_sleep(1); \
;     if ((++_sp & 255u) == 0u) { if (xb_ld(&(bar)[XB_TMO])) break; if (_sp > XB_SPIN_CAP) { atomicAdd(&(bar)[XB_TMO], 1u); break; } } } } while (0)
; __device__ __forceinline__ void xcd_barrier(const XcdBarrier& b) {
;     ...
;             XB_SPIN(xb_ld(&bar[XB_XGEN(b.x)]) == gen, bar);
;             __builtin_amdgcn_fence(__ATOMIC_ACQUIRE, "agent");
;             asm volatile("s_waitcnt vmcnt(0)" ::: "memory");
.LBB0_1217:
	s_or_b64 exec, exec, s[12:13]
	s_waitcnt vmcnt(0)
	s_waitcnt vmcnt(0)
